# filter MLP layers 1-2: all LDS reads of a loop trip issued before the fma chains (same chains, bit-identical); plus the attention DPP/permlane shuffles
# speedup vs baseline: 1.0017x; 1.0017x over previous
; __device__ __forceinline__ void ph_filtergen(KP p, int l, unsigned char* sm, int wv) {
;     ...
;         {
;             float a[8];
; #pragma unroll
;             for (int i = 0; i < 8; ++i) a[i] = b1[wid * 8 + i];
; #pragma unroll 3
;             for (int f = 0; f < 33; ++f) {
;                 const float zv = zf[lane * 34 + f];
;                 const f32x4 w0 = *(const f32x4*)(w1s + f * 64 + wid * 8), w1v = *(const f32x4*)(w1s + f * 64 + wid * 8 + 4);
;                 a[0] += zv * w0.x; a[1] += zv * w0.y; a[2] += zv * w0.z; a[3] += zv * w0.w; a[4] += zv * w1v.x; a[5] += zv * w1v.y; a[6] += zv * w1v.z; a[7] += zv * w1v.w;
;             }
; #pragma unroll
;             for (int i = 0; i < 8; ++i) h1[lane * 65 + wid * 8 + i] = sinpif(f1[wid * 8 + i] * a[i] * 0.3183098861837907f);
.LBB0_887:
	v_add_u32_e32 v7, s0, v31
	ds_read2_b32 v[38:39], v7 offset1:1
	ds_read_b32 v36, v7 offset:8
	ds_read_b128 v[96:99], v6
	ds_read_b128 v[100:103], v6 offset:16
	ds_read_b128 v[104:107], v6 offset:256
	ds_read_b128 v[108:111], v6 offset:272
	ds_read_b128 v[112:115], v6 offset:512
	ds_read_b128 v[116:119], v6 offset:528
	s_add_i32 s0, s0, 12
	s_cmpk_eq_i32 s0, 0x84
	v_add_u32_e32 v6, 0x300, v6
	s_waitcnt lgkmcnt(5)
	v_pk_fma_f32 v[10:11], v[38:39], v[96:97], v[10:11] op_sel_hi:[0,1,1]
	v_pk_fma_f32 v[12:13], v[38:39], v[98:99], v[12:13] op_sel_hi:[0,1,1]
	s_waitcnt lgkmcnt(4)
	v_pk_fma_f32 v[2:3], v[38:39], v[100:101], v[2:3] op_sel_hi:[0,1,1]
	v_pk_fma_f32 v[4:5], v[38:39], v[102:103], v[4:5] op_sel_hi:[0,1,1]
	s_waitcnt lgkmcnt(3)
	v_pk_fma_f32 v[10:11], v[38:39], v[104:105], v[10:11] op_sel:[1,0,0]
	v_pk_fma_f32 v[12:13], v[38:39], v[106:107], v[12:13] op_sel:[1,0,0]
	s_waitcnt lgkmcnt(2)
	v_pk_fma_f32 v[2:3], v[38:39], v[108:109], v[2:3] op_sel:[1,0,0]
	v_pk_fma_f32 v[4:5], v[38:39], v[110:111], v[4:5] op_sel:[1,0,0]
	s_waitcnt lgkmcnt(1)
	v_pk_fma_f32 v[10:11], v[36:37], v[112:113], v[10:11] op_sel_hi:[0,1,1]
	v_pk_fma_f32 v[12:13], v[36:37], v[114:115], v[12:13] op_sel_hi:[0,1,1]
	s_waitcnt lgkmcnt(0)
	v_pk_fma_f32 v[2:3], v[36:37], v[116:117], v[2:3] op_sel_hi:[0,1,1]
	v_pk_fma_f32 v[4:5], v[36:37], v[118:119], v[4:5] op_sel_hi:[0,1,1]
	s_cbranch_scc0 .LBB0_887
	v_mov_b32_e32 v6, v156
	v_mov_b32_e32 v7, v157
	v_mov_b32_e32 v8, v158
	v_mov_b32_e32 v9, v159
	v_mov_b32_e32 v14, v152
	v_mov_b32_e32 v15, v153
	v_mov_b32_e32 v16, v154
	v_mov_b32_e32 v17, v155
	s_mov_b32 s18, 0x3ea2f983
	s_mov_b32 s36, 0x3e75aa41
	s_mov_b32 s38, 0x40234736
	s_mov_b32 s40, 0xc0a55e0e
	s_mov_b32 s42, 0x40490fdb
	s_mov_b32 s44, 0x3d4be544
	s_mov_b32 s46, 0xbfaad1da
	s_mov_b32 s48, 0x4081e0d3
	s_mov_b32 s50, 0xc09de9e6
	s_mov_b32 s15, 0
	v_pk_mul_f32 v[2:3], v[2:3], v[6:7]
	v_pk_mul_f32 v[10:11], v[10:11], v[14:15]
	v_pk_mul_f32 v[12:13], v[12:13], v[16:17]
	v_pk_mul_f32 v[34:35], v[10:11], s[18:19] op_sel_hi:[1,0]
	v_pk_mul_f32 v[12:13], v[12:13], s[18:19] op_sel_hi:[1,0]
	v_and_b32_e32 v37, 0x7fffffff, v35
	v_and_b32_e32 v36, 0x7fffffff, v34
	v_pk_mul_f32 v[10:11], v[36:37], 0.5 op_sel_hi:[1,0]
	v_cmp_gt_f32_e64 s[16:17], |v35|, 1.0
	v_floor_f32_e32 v14, v10
	v_floor_f32_e32 v15, v11
	v_sub_f32_e32 v14, v10, v14
	v_sub_f32_e32 v15, v11, v15
	v_min_f32_e32 v14, 0x3f7fffff, v14
	v_min_f32_e32 v15, 0x3f7fffff, v15
	v_cmp_u_f32_e32 vcc, v10, v10
	v_cmp_u_f32_e64 s[0:1], v11, v11
	v_xor_b32_e32 v37, v37, v35
	v_cndmask_b32_e32 v14, v14, v10, vcc
	v_cndmask_b32_e64 v15, v15, v11, s[0:1]
	v_cmp_class_f32_e32 vcc, v11, v239
	v_cmp_class_f32_e64 s[0:1], v10, v239
	v_pk_add_f32 v[10:11], v[14:15], v[14:15]
	v_xor_b32_e32 v36, v36, v34
	v_cndmask_b32_e64 v10, v10, 0, s[0:1]
	v_cndmask_b32_e64 v11, v11, 0, vcc
	v_cmp_gt_f32_e64 s[0:1], |v34|, 1.0
	v_cndmask_b32_e64 v11, |v35|, v11, s[16:17]
	v_add_f32_e32 v15, v11, v11
	v_cndmask_b32_e64 v10, |v34|, v10, s[0:1]
	v_add_f32_e32 v14, v10, v10
	v_rndne_f32_e32 v14, v14
	v_rndne_f32_e32 v15, v15
	v_pk_fma_f32 v[38:39], v[14:15], -0.5, v[10:11] op_sel_hi:[1,0,1]
	s_mov_b32 s0, 0xbf1f24be
	v_pk_mul_f32 v[40:41], v[38:39], v[38:39]
	v_mov_b64_e32 v[10:11], s[0:1]
	v_cvt_i32_f32_e32 v33, v15
	v_cvt_i32_f32_e32 v44, v14
	v_pk_fma_f32 v[14:15], v[40:41], s[36:37], v[10:11] op_sel_hi:[1,0,0]
	v_pk_mul_f32 v[42:43], v[38:39], v[40:41]
	v_pk_fma_f32 v[14:15], v[40:41], v[14:15], s[38:39] op_sel_hi:[1,1,0]
	s_mov_b32 s0, 0x3e642e9d
	v_pk_fma_f32 v[14:15], v[40:41], v[14:15], s[40:41] op_sel_hi:[1,1,0]
	v_and_b32_e32 v17, 0x7fffffff, v13
	v_pk_mul_f32 v[14:15], v[42:43], v[14:15]
	v_and_b32_e32 v16, 0x7fffffff, v12
	v_pk_fma_f32 v[38:39], v[38:39], s[42:43], v[14:15] op_sel_hi:[1,0,1]
	v_mov_b64_e32 v[14:15], s[0:1]
	v_pk_fma_f32 v[42:43], v[40:41], s[44:45], v[14:15] op_sel_hi:[1,0,0]
	v_cmp_gt_f32_e64 s[16:17], |v13|, 1.0
	v_pk_fma_f32 v[42:43], v[40:41], v[42:43], s[46:47] op_sel_hi:[1,1,0]
	v_pk_mul_f32 v[2:3], v[2:3], s[18:19] op_sel_hi:[1,0]
	v_pk_fma_f32 v[42:43], v[40:41], v[42:43], s[48:49] op_sel_hi:[1,1,0]
	v_and_b32_e32 v7, 0x7fffffff, v3
	v_pk_fma_f32 v[42:43], v[40:41], v[42:43], s[50:51] op_sel_hi:[1,1,0]
	v_and_b32_e32 v6, 0x7fffffff, v2
	v_pk_fma_f32 v[40:41], v[40:41], v[42:43], 1.0 op_sel_hi:[1,1,0]
	v_and_b32_e32 v43, 1, v44
	v_cmp_eq_u32_e32 vcc, 0, v43
	v_and_b32_e32 v42, 1, v33
	v_lshlrev_b32_e32 v33, 30, v33
	v_cndmask_b32_e32 v38, v40, v38, vcc
	v_lshlrev_b32_e32 v40, 30, v44
	v_cmp_eq_u32_e64 s[0:1], 0, v42
	v_and_b32_e32 v33, 0x80000000, v33
	v_and_b32_e32 v40, 0x80000000, v40
	v_cndmask_b32_e64 v39, v41, v39, s[0:1]
	v_xor_b32_e32 v33, v37, v33
	v_xor_b32_e32 v36, v36, v40
	v_xor_b32_e32 v33, v33, v39
	v_xor_b32_e32 v36, v36, v38
	v_cmp_class_f32_e32 vcc, v34, v242
	v_cmp_class_f32_e64 s[0:1], v35, v242
	v_add_u32_e32 v35, 0x2200, v86
	v_cndmask_b32_e32 v34, v204, v36, vcc
	v_cndmask_b32_e64 v33, v204, v33, s[0:1]
	ds_write2_b32 v35, v34, v33 offset1:1
	v_pk_mul_f32 v[34:35], v[16:17], 0.5 op_sel_hi:[1,0]
	v_xor_b32_e32 v17, v17, v13
	v_floor_f32_e32 v33, v34
	v_floor_f32_e32 v36, v35
	v_sub_f32_e32 v33, v34, v33
	v_sub_f32_e32 v36, v35, v36
	v_min_f32_e32 v33, 0x3f7fffff, v33
	v_min_f32_e32 v36, 0x3f7fffff, v36
	v_cmp_u_f32_e32 vcc, v34, v34
	v_cmp_u_f32_e64 s[0:1], v35, v35
	v_xor_b32_e32 v16, v16, v12
	s_nop 0
	v_cndmask_b32_e64 v37, v36, v35, s[0:1]
	v_cndmask_b32_e32 v36, v33, v34, vcc
	v_cmp_class_f32_e32 vcc, v35, v239
	v_cmp_class_f32_e64 s[0:1], v34, v239
	v_pk_add_f32 v[34:35], v[36:37], v[36:37]
	s_nop 0
	v_cndmask_b32_e64 v33, v34, 0, s[0:1]
	v_cndmask_b32_e64 v34, v35, 0, vcc
; __device__ __forceinline__ void ph_filtergen(KP p, int l, unsigned char* sm, int wv) {
;     ...
; #pragma unroll
;             for (int i = 0; i < 8; ++i) h1[lane * 65 + wid * 8 + i] = sinpif(f1[wid * 8 + i] * a[i] * 0.3183098861837907f);
	v_cmp_gt_f32_e64 s[0:1], |v12|, 1.0
	v_cndmask_b32_e64 v35, |v13|, v34, s[16:17]
	v_cmp_gt_f32_e64 s[16:17], |v3|, 1.0
	v_cndmask_b32_e64 v34, |v12|, v33, s[0:1]
	v_add_f32_e32 v33, v34, v34
	v_rndne_f32_e32 v36, v33
	v_add_f32_e32 v33, v35, v35
	v_rndne_f32_e32 v37, v33
	v_pk_fma_f32 v[34:35], v[36:37], -0.5, v[34:35] op_sel_hi:[1,0,1]
	v_cvt_i32_f32_e32 v33, v37
	v_cvt_i32_f32_e32 v42, v36
	v_pk_mul_f32 v[36:37], v[34:35], v[34:35]
	s_nop 0
	v_pk_fma_f32 v[38:39], v[36:37], s[36:37], v[10:11] op_sel_hi:[1,0,0]
	v_pk_mul_f32 v[40:41], v[34:35], v[36:37]
	v_pk_fma_f32 v[38:39], v[36:37], v[38:39], s[38:39] op_sel_hi:[1,1,0]
	s_nop 0
	v_pk_fma_f32 v[38:39], v[36:37], v[38:39], s[40:41] op_sel_hi:[1,1,0]
	s_nop 0
	v_pk_mul_f32 v[38:39], v[40:41], v[38:39]
	s_nop 0
	v_pk_fma_f32 v[34:35], v[34:35], s[42:43], v[38:39] op_sel_hi:[1,0,1]
	v_pk_fma_f32 v[38:39], v[36:37], s[44:45], v[14:15] op_sel_hi:[1,0,0]
	s_nop 0
	v_pk_fma_f32 v[38:39], v[36:37], v[38:39], s[46:47] op_sel_hi:[1,1,0]
	s_nop 0
	v_pk_fma_f32 v[38:39], v[36:37], v[38:39], s[48:49] op_sel_hi:[1,1,0]
	s_nop 0
	v_pk_fma_f32 v[38:39], v[36:37], v[38:39], s[50:51] op_sel_hi:[1,1,0]
	s_nop 0
	v_pk_fma_f32 v[36:37], v[36:37], v[38:39], 1.0 op_sel_hi:[1,1,0]
	v_and_b32_e32 v39, 1, v42
	v_cmp_eq_u32_e32 vcc, 0, v39
	v_and_b32_e32 v38, 1, v33
	v_lshlrev_b32_e32 v33, 30, v33
	v_cndmask_b32_e32 v34, v36, v34, vcc
	v_lshlrev_b32_e32 v36, 30, v42
	v_cmp_eq_u32_e64 s[0:1], 0, v38
	v_and_b32_e32 v33, 0x80000000, v33
	v_and_b32_e32 v36, 0x80000000, v36
	v_cndmask_b32_e64 v35, v37, v35, s[0:1]
	v_xor_b32_e32 v17, v17, v33
	v_xor_b32_e32 v16, v16, v36
	v_xor_b32_e32 v17, v17, v35
	v_xor_b32_e32 v16, v16, v34
	v_cmp_class_f32_e32 vcc, v12, v242
	v_cmp_class_f32_e64 s[0:1], v13, v242
	s_nop 0
	v_cndmask_b32_e32 v13, v204, v16, vcc
	v_cndmask_b32_e64 v12, v204, v17, s[0:1]
	v_add_u32_e32 v16, 0x2208, v86
	ds_write2_b32 v16, v13, v12 offset1:1
	v_pk_mul_f32 v[12:13], v[6:7], 0.5 op_sel_hi:[1,0]
	v_xor_b32_e32 v7, v7, v3
	v_floor_f32_e32 v16, v12
	v_floor_f32_e32 v17, v13
	v_sub_f32_e32 v16, v12, v16
	v_sub_f32_e32 v17, v13, v17
	v_min_f32_e32 v16, 0x3f7fffff, v16
	v_min_f32_e32 v17, 0x3f7fffff, v17
	v_cmp_u_f32_e32 vcc, v12, v12
	v_cmp_u_f32_e64 s[0:1], v13, v13
	v_xor_b32_e32 v6, v6, v2
	v_cndmask_b32_e32 v16, v16, v12, vcc
	v_cndmask_b32_e64 v17, v17, v13, s[0:1]
	v_cmp_class_f32_e32 vcc, v13, v239
	v_cmp_class_f32_e64 s[0:1], v12, v239
	v_pk_add_f32 v[12:13], v[16:17], v[16:17]
	s_nop 0
	v_cndmask_b32_e64 v12, v12, 0, s[0:1]
	v_cndmask_b32_e64 v13, v13, 0, vcc
	v_cmp_gt_f32_e64 s[0:1], |v2|, 1.0
	v_cndmask_b32_e64 v13, |v3|, v13, s[16:17]
	v_add_f32_e32 v17, v13, v13
	v_cndmask_b32_e64 v12, |v2|, v12, s[0:1]
	v_add_f32_e32 v16, v12, v12
	v_rndne_f32_e32 v16, v16
	v_rndne_f32_e32 v17, v17
	v_pk_fma_f32 v[12:13], v[16:17], -0.5, v[12:13] op_sel_hi:[1,0,1]
	v_cvt_i32_f32_e32 v33, v17
	v_cvt_i32_f32_e32 v38, v16
	v_pk_mul_f32 v[16:17], v[12:13], v[12:13]
	s_nop 0
	v_pk_fma_f32 v[34:35], v[16:17], s[36:37], v[10:11] op_sel_hi:[1,0,0]
	v_pk_mul_f32 v[36:37], v[12:13], v[16:17]
	v_pk_fma_f32 v[34:35], v[16:17], v[34:35], s[38:39] op_sel_hi:[1,1,0]
	s_nop 0
	v_pk_fma_f32 v[34:35], v[16:17], v[34:35], s[40:41] op_sel_hi:[1,1,0]
	s_nop 0
	v_pk_mul_f32 v[34:35], v[36:37], v[34:35]
	s_nop 0
	v_pk_fma_f32 v[12:13], v[12:13], s[42:43], v[34:35] op_sel_hi:[1,0,1]
	v_pk_fma_f32 v[34:35], v[16:17], s[44:45], v[14:15] op_sel_hi:[1,0,0]
	s_nop 0
	v_pk_fma_f32 v[34:35], v[16:17], v[34:35], s[46:47] op_sel_hi:[1,1,0]
	s_nop 0
	v_pk_fma_f32 v[34:35], v[16:17], v[34:35], s[48:49] op_sel_hi:[1,1,0]
	s_nop 0
	v_pk_fma_f32 v[34:35], v[16:17], v[34:35], s[50:51] op_sel_hi:[1,1,0]
	s_nop 0
	v_pk_fma_f32 v[16:17], v[16:17], v[34:35], 1.0 op_sel_hi:[1,1,0]
	v_and_b32_e32 v34, 1, v33
	v_and_b32_e32 v35, 1, v38
	v_cmp_eq_u32_e32 vcc, 0, v35
	v_cmp_eq_u32_e64 s[0:1], 0, v34
	s_nop 0
	v_cndmask_b32_e32 v12, v16, v12, vcc
	v_cndmask_b32_e64 v13, v17, v13, s[0:1]
	v_lshlrev_b32_e32 v16, 30, v33
	v_lshlrev_b32_e32 v17, 30, v38
	v_and_b32_e32 v16, 0x80000000, v16
	v_and_b32_e32 v17, 0x80000000, v17
	v_xor_b32_e32 v7, v7, v16
	v_xor_b32_e32 v6, v6, v17
	v_xor_b32_e32 v7, v7, v13
	v_xor_b32_e32 v6, v6, v12
	v_cmp_class_f32_e32 vcc, v2, v242
	v_cmp_class_f32_e64 s[0:1], v3, v242
	s_nop 0
	v_cndmask_b32_e32 v3, v204, v6, vcc
	v_cndmask_b32_e64 v2, v204, v7, s[0:1]
	v_add_u32_e32 v6, 0x2210, v86
	ds_write2_b32 v6, v3, v2 offset1:1
	v_pk_mul_f32 v[2:3], v[4:5], v[8:9]
	s_nop 0
	v_pk_mul_f32 v[2:3], v[2:3], s[18:19] op_sel_hi:[1,0]
	s_nop 0
	v_and_b32_e32 v5, 0x7fffffff, v3
	v_and_b32_e32 v4, 0x7fffffff, v2
	v_pk_mul_f32 v[6:7], v[4:5], 0.5 op_sel_hi:[1,0]
	v_cmp_gt_f32_e64 s[16:17], |v3|, 1.0
	v_floor_f32_e32 v8, v6
	v_floor_f32_e32 v9, v7
	v_sub_f32_e32 v8, v6, v8
	v_sub_f32_e32 v9, v7, v9
	v_min_f32_e32 v8, 0x3f7fffff, v8
	v_min_f32_e32 v9, 0x3f7fffff, v9
	v_cmp_u_f32_e32 vcc, v6, v6
	v_cmp_u_f32_e64 s[0:1], v7, v7
	v_xor_b32_e32 v5, v5, v3
	v_cndmask_b32_e32 v8, v8, v6, vcc
	v_cndmask_b32_e64 v9, v9, v7, s[0:1]
	v_cmp_class_f32_e32 vcc, v7, v239
	v_cmp_class_f32_e64 s[0:1], v6, v239
	v_pk_add_f32 v[6:7], v[8:9], v[8:9]
	v_xor_b32_e32 v4, v4, v2
	v_cndmask_b32_e64 v6, v6, 0, s[0:1]
	v_cndmask_b32_e64 v7, v7, 0, vcc
	v_cmp_gt_f32_e64 s[0:1], |v2|, 1.0
	v_cndmask_b32_e64 v7, |v3|, v7, s[16:17]
	v_add_f32_e32 v9, v7, v7
	v_cndmask_b32_e64 v6, |v2|, v6, s[0:1]
	v_add_f32_e32 v8, v6, v6
	v_rndne_f32_e32 v8, v8
	v_rndne_f32_e32 v9, v9
	v_pk_fma_f32 v[6:7], v[8:9], -0.5, v[6:7] op_sel_hi:[1,0,1]
	v_cvt_i32_f32_e32 v16, v9
	v_cvt_i32_f32_e32 v17, v8
	v_pk_mul_f32 v[8:9], v[6:7], v[6:7]
	s_nop 0
	v_pk_fma_f32 v[10:11], v[8:9], s[36:37], v[10:11] op_sel_hi:[1,0,0]
	v_pk_mul_f32 v[12:13], v[6:7], v[8:9]
	v_pk_fma_f32 v[10:11], v[8:9], v[10:11], s[38:39] op_sel_hi:[1,1,0]
	s_nop 0
	v_pk_fma_f32 v[10:11], v[8:9], v[10:11], s[40:41] op_sel_hi:[1,1,0]
	s_nop 0
	v_pk_mul_f32 v[10:11], v[12:13], v[10:11]
	s_nop 0
	v_pk_fma_f32 v[6:7], v[6:7], s[42:43], v[10:11] op_sel_hi:[1,0,1]
	v_pk_fma_f32 v[10:11], v[8:9], s[44:45], v[14:15] op_sel_hi:[1,0,0]
	s_nop 0
	v_pk_fma_f32 v[10:11], v[8:9], v[10:11], s[46:47] op_sel_hi:[1,1,0]
	s_nop 0
	v_pk_fma_f32 v[10:11], v[8:9], v[10:11], s[48:49] op_sel_hi:[1,1,0]
	s_nop 0
	v_pk_fma_f32 v[10:11], v[8:9], v[10:11], s[50:51] op_sel_hi:[1,1,0]
	s_nop 0
	v_pk_fma_f32 v[8:9], v[8:9], v[10:11], 1.0 op_sel_hi:[1,1,0]
	v_and_b32_e32 v10, 1, v16
	v_and_b32_e32 v11, 1, v17
	v_cmp_eq_u32_e32 vcc, 0, v11
	v_cmp_eq_u32_e64 s[0:1], 0, v10
	s_nop 0
	v_cndmask_b32_e32 v6, v8, v6, vcc
	v_cndmask_b32_e64 v7, v9, v7, s[0:1]
	v_lshlrev_b32_e32 v8, 30, v16
	v_lshlrev_b32_e32 v9, 30, v17
	v_and_b32_e32 v8, 0x80000000, v8
	v_and_b32_e32 v9, 0x80000000, v9
	v_xor_b32_e32 v5, v5, v8
	v_xor_b32_e32 v4, v4, v9
	v_xor_b32_e32 v5, v5, v7
	v_xor_b32_e32 v4, v4, v6
	v_cmp_class_f32_e32 vcc, v2, v242
	v_cmp_class_f32_e64 s[0:1], v3, v242
	v_mov_b32_e32 v6, v91
	v_cndmask_b32_e32 v3, v204, v4, vcc
	v_cndmask_b32_e64 v2, v204, v5, s[0:1]
	v_add_u32_e32 v4, 0x2218, v86
	ds_write2_b32 v4, v3, v2 offset1:1
	s_waitcnt lgkmcnt(0)
; __device__ __forceinline__ void ph_filtergen(KP p, int l, unsigned char* sm, int wv) {
;     ...
;         __syncthreads();
;         {
;             float a[8];
; #pragma unroll
;             for (int i = 0; i < 8; ++i) a[i] = b2[wid * 8 + i];
; #pragma unroll 4
;             for (int j = 0; j < 64; ++j) {
;                 const float zv = h1[lane * 65 + j];
;                 const f32x4 w0 = *(const f32x4*)(w2s + j * 64 + wid * 8), w1v = *(const f32x4*)(w2s + j * 64 + wid * 8 + 4);
;                 a[0] += zv * w0.x; a[1] += zv * w0.y; a[2] += zv * w0.z; a[3] += zv * w0.w; a[4] += zv * w1v.x; a[5] += zv * w1v.y; a[6] += zv * w1v.z; a[7] += zv * w1v.w;
;             }
; #pragma unroll
;             for (int i = 0; i < 8; ++i) h2[lane * 68 + wid * 8 + i] = sinpif(f2[wid * 8 + i] * a[i] * 0.3183098861837907f);
	s_barrier
	v_mov_b32_e32 v10, v160
	v_mov_b32_e32 v11, v161
	v_mov_b32_e32 v12, v162
	v_mov_b32_e32 v13, v163
	v_mov_b32_e32 v2, v164
	v_mov_b32_e32 v3, v165
	v_mov_b32_e32 v4, v166
	v_mov_b32_e32 v5, v167
.LBB0_889:
	v_add_u32_e32 v7, s15, v90
	ds_read2_b32 v[38:39], v7 offset1:1
	ds_read2_b32 v[36:37], v7 offset0:2 offset1:3
	ds_read_b128 v[96:99], v6
	ds_read_b128 v[100:103], v6 offset:16
	ds_read_b128 v[104:107], v6 offset:256
	ds_read_b128 v[108:111], v6 offset:272
	ds_read_b128 v[112:115], v6 offset:512
	ds_read_b128 v[116:119], v6 offset:528
	ds_read_b128 v[120:123], v6 offset:768
	ds_read_b128 v[124:127], v6 offset:784
	s_add_i32 s15, s15, 16
	s_cmpk_eq_i32 s15, 0x100
	v_add_u32_e32 v6, 0x400, v6
	s_waitcnt lgkmcnt(7)
	v_pk_fma_f32 v[10:11], v[38:39], v[96:97], v[10:11] op_sel_hi:[0,1,1]
	v_pk_fma_f32 v[12:13], v[38:39], v[98:99], v[12:13] op_sel_hi:[0,1,1]
	s_waitcnt lgkmcnt(6)
	v_pk_fma_f32 v[2:3], v[38:39], v[100:101], v[2:3] op_sel_hi:[0,1,1]
	v_pk_fma_f32 v[4:5], v[38:39], v[102:103], v[4:5] op_sel_hi:[0,1,1]
	s_waitcnt lgkmcnt(5)
	v_pk_fma_f32 v[10:11], v[38:39], v[104:105], v[10:11] op_sel:[1,0,0]
	v_pk_fma_f32 v[12:13], v[38:39], v[106:107], v[12:13] op_sel:[1,0,0]
	s_waitcnt lgkmcnt(4)
	v_pk_fma_f32 v[2:3], v[38:39], v[108:109], v[2:3] op_sel:[1,0,0]
	v_pk_fma_f32 v[4:5], v[38:39], v[110:111], v[4:5] op_sel:[1,0,0]
	s_waitcnt lgkmcnt(3)
	v_pk_fma_f32 v[10:11], v[36:37], v[112:113], v[10:11] op_sel_hi:[0,1,1]
	v_pk_fma_f32 v[12:13], v[36:37], v[114:115], v[12:13] op_sel_hi:[0,1,1]
	s_waitcnt lgkmcnt(2)
	v_pk_fma_f32 v[2:3], v[36:37], v[116:117], v[2:3] op_sel_hi:[0,1,1]
	v_pk_fma_f32 v[4:5], v[36:37], v[118:119], v[4:5] op_sel_hi:[0,1,1]
	s_waitcnt lgkmcnt(1)
	v_pk_fma_f32 v[10:11], v[36:37], v[120:121], v[10:11] op_sel:[1,0,0]
	v_pk_fma_f32 v[12:13], v[36:37], v[122:123], v[12:13] op_sel:[1,0,0]
	s_waitcnt lgkmcnt(0)
	v_pk_fma_f32 v[2:3], v[36:37], v[124:125], v[2:3] op_sel:[1,0,0]
	v_pk_fma_f32 v[4:5], v[36:37], v[126:127], v[4:5] op_sel:[1,0,0]
	s_cbranch_scc0 .LBB0_889
	v_mov_b32_e32 v34, v168
	v_mov_b32_e32 v35, v169
	v_mov_b32_e32 v36, v170
	v_mov_b32_e32 v37, v171
	v_mov_b32_e32 v6, v172
	v_mov_b32_e32 v7, v173
	v_mov_b32_e32 v8, v174
	v_mov_b32_e32 v9, v175
	s_mov_b32 s18, 0x3ea2f983
	s_and_b64 s[0:1], s[8:9], exec
	s_mov_b32 s0, 0xbf1f24be
	v_mov_b64_e32 v[14:15], s[0:1]
	s_mov_b32 s0, 0x3e642e9d
	v_mov_b64_e32 v[16:17], s[0:1]
	s_cselect_b32 s0, 0, 0x2000000
	s_add_u32 s16, s12, s0
	s_mov_b32 s36, 0x3e75aa41
	s_mov_b32 s44, 0x3d4be544
	s_mov_b32 s38, 0x40234736
	s_mov_b32 s46, 0xbfaad1da
	s_mov_b32 s40, 0xc0a55e0e
	s_mov_b32 s48, 0x4081e0d3
	s_mov_b32 s50, 0xc09de9e6
	s_mov_b32 s42, 0x40490fdb
	s_addc_u32 s17, s13, 0
	s_and_b32 s31, s32, 1
	s_lshl_b32 s31, s31, 1
	s_mov_b32 s15, s72
	v_pk_mul_f32 v[10:11], v[10:11], v[34:35]
	s_nop 0
	v_pk_mul_f32 v[34:35], v[10:11], s[18:19] op_sel_hi:[1,0]
	v_pk_mul_f32 v[12:13], v[12:13], v[36:37]
	v_and_b32_e32 v37, 0x7fffffff, v35
	v_and_b32_e32 v36, 0x7fffffff, v34
	v_pk_mul_f32 v[10:11], v[12:13], s[18:19] op_sel_hi:[1,0]
	v_pk_mul_f32 v[38:39], v[36:37], 0.5 op_sel_hi:[1,0]
	v_and_b32_e32 v13, 0x7fffffff, v11
	v_and_b32_e32 v12, 0x7fffffff, v10
	v_floor_f32_e32 v41, v39
	v_xor_b32_e32 v33, v37, v35
	v_xor_b32_e32 v48, v36, v34
	v_pk_mul_f32 v[36:37], v[12:13], 0.5 op_sel_hi:[1,0]
	v_floor_f32_e32 v40, v38
	v_sub_f32_e32 v41, v39, v41
	v_floor_f32_e32 v43, v37
	v_sub_f32_e32 v40, v38, v40
	v_min_f32_e32 v41, 0x3f7fffff, v41
	v_cmp_u_f32_e32 vcc, v39, v39
	v_floor_f32_e32 v42, v36
	v_sub_f32_e32 v43, v37, v43
	v_min_f32_e32 v40, 0x3f7fffff, v40
	v_cndmask_b32_e32 v41, v41, v39, vcc
	v_cmp_u_f32_e32 vcc, v38, v38
	v_sub_f32_e32 v42, v36, v42
	v_min_f32_e32 v43, 0x3f7fffff, v43
	v_cndmask_b32_e32 v40, v40, v38, vcc
	v_cmp_u_f32_e32 vcc, v37, v37
	v_min_f32_e32 v42, 0x3f7fffff, v42
	v_pk_add_f32 v[40:41], v[40:41], v[40:41]
	v_cndmask_b32_e32 v43, v43, v37, vcc
	v_cmp_u_f32_e32 vcc, v36, v36
	v_cmp_gt_f32_e64 s[0:1], |v35|, 1.0
	v_xor_b32_e32 v13, v13, v11
	v_cndmask_b32_e32 v42, v42, v36, vcc
	v_cmp_class_f32_e32 vcc, v38, v239
	v_pk_add_f32 v[42:43], v[42:43], v[42:43]
	v_pk_mul_f32 v[2:3], v[2:3], v[6:7]
	v_cndmask_b32_e64 v38, v40, 0, vcc
	v_cmp_class_f32_e32 vcc, v39, v239
	v_pk_mul_f32 v[2:3], v[2:3], s[18:19] op_sel_hi:[1,0]
	v_xor_b32_e32 v12, v12, v10
	v_cndmask_b32_e64 v39, v41, 0, vcc
	v_cmp_class_f32_e32 vcc, v36, v239
	v_and_b32_e32 v7, 0x7fffffff, v3
	v_and_b32_e32 v6, 0x7fffffff, v2
	v_cndmask_b32_e64 v40, v42, 0, vcc
	v_cmp_class_f32_e32 vcc, v37, v239
	v_cndmask_b32_e64 v37, |v35|, v39, s[0:1]
	v_cmp_gt_f32_e64 s[0:1], |v34|, 1.0
	v_cndmask_b32_e64 v41, v43, 0, vcc
	v_pk_mul_f32 v[4:5], v[4:5], v[8:9]
	v_cndmask_b32_e64 v36, |v34|, v38, s[0:1]
	v_cmp_gt_f32_e64 s[0:1], |v11|, 1.0
	v_pk_mul_f32 v[4:5], v[4:5], s[18:19] op_sel_hi:[1,0]
	s_lshl_b32 s18, s14, 1
	v_cndmask_b32_e64 v39, |v11|, v41, s[0:1]
	v_cmp_gt_f32_e64 s[0:1], |v10|, 1.0
	v_add_f32_e32 v41, v37, v37
	v_rndne_f32_e32 v41, v41
	v_cndmask_b32_e64 v38, |v10|, v40, s[0:1]
	v_add_f32_e32 v40, v36, v36
	v_rndne_f32_e32 v40, v40
	v_add_f32_e32 v42, v38, v38
	v_add_f32_e32 v43, v39, v39
	v_pk_fma_f32 v[36:37], v[40:41], -0.5, v[36:37] op_sel_hi:[1,0,1]
	v_rndne_f32_e32 v42, v42
	v_rndne_f32_e32 v43, v43
	v_cvt_i32_f32_e32 v49, v41
	v_cvt_i32_f32_e32 v50, v40
	v_pk_mul_f32 v[40:41], v[36:37], v[36:37]
	v_pk_fma_f32 v[38:39], v[42:43], -0.5, v[38:39] op_sel_hi:[1,0,1]
	v_cvt_i32_f32_e32 v51, v43
	v_cvt_i32_f32_e32 v52, v42
	v_pk_fma_f32 v[42:43], v[40:41], s[36:37], v[14:15] op_sel_hi:[1,0,0]
	v_pk_fma_f32 v[46:47], v[40:41], s[44:45], v[16:17] op_sel_hi:[1,0,0]
	v_pk_fma_f32 v[42:43], v[40:41], v[42:43], s[38:39] op_sel_hi:[1,1,0]
; __device__ __forceinline__ void ph_filtergen(KP p, int l, unsigned char* sm, int wv) {
;     ...
; #pragma unroll
;             for (int i = 0; i < 8; ++i) h2[lane * 68 + wid * 8 + i] = sinpif(f2[wid * 8 + i] * a[i] * 0.3183098861837907f);
	v_pk_fma_f32 v[46:47], v[40:41], v[46:47], s[46:47] op_sel_hi:[1,1,0]
	v_pk_mul_f32 v[44:45], v[36:37], v[40:41]
	v_pk_fma_f32 v[42:43], v[40:41], v[42:43], s[40:41] op_sel_hi:[1,1,0]
	v_pk_fma_f32 v[46:47], v[40:41], v[46:47], s[48:49] op_sel_hi:[1,1,0]
	v_and_b32_e32 v53, 1, v49
	v_lshlrev_b32_e32 v49, 30, v49
	v_pk_mul_f32 v[42:43], v[44:45], v[42:43]
	v_pk_fma_f32 v[44:45], v[40:41], v[46:47], s[50:51] op_sel_hi:[1,1,0]
	v_and_b32_e32 v54, 1, v50
	v_lshlrev_b32_e32 v50, 30, v50
	v_and_b32_e32 v46, 0x80000000, v49
	v_pk_fma_f32 v[36:37], v[36:37], s[42:43], v[42:43] op_sel_hi:[1,0,1]
	v_pk_fma_f32 v[40:41], v[40:41], v[44:45], 1.0 op_sel_hi:[1,1,0]
	v_cmp_eq_u32_e32 vcc, 0, v53
	v_and_b32_e32 v47, 0x80000000, v50
	v_xor_b32_e32 v33, v33, v46
	v_cndmask_b32_e32 v37, v41, v37, vcc
	v_cmp_eq_u32_e32 vcc, 0, v54
	v_xor_b32_e32 v42, v48, v47
	v_xor_b32_e32 v33, v33, v37
	v_cndmask_b32_e32 v36, v40, v36, vcc
	v_cmp_class_f32_e32 vcc, v35, v242
	v_xor_b32_e32 v36, v42, v36
	v_cmp_gt_f32_e64 s[0:1], |v3|, 1.0
	v_cndmask_b32_e32 v35, v204, v33, vcc
	v_cmp_class_f32_e32 vcc, v34, v242
	v_and_b32_e32 v33, 1, v51
	s_nop 0
	v_cndmask_b32_e32 v34, v204, v36, vcc
	v_pk_mul_f32 v[36:37], v[38:39], v[38:39]
	v_cmp_eq_u32_e32 vcc, 0, v33
	v_pk_fma_f32 v[40:41], v[36:37], s[36:37], v[14:15] op_sel_hi:[1,0,0]
	v_pk_mul_f32 v[42:43], v[38:39], v[36:37]
	v_pk_fma_f32 v[40:41], v[36:37], v[40:41], s[38:39] op_sel_hi:[1,1,0]
	s_nop 0
	v_pk_fma_f32 v[40:41], v[36:37], v[40:41], s[40:41] op_sel_hi:[1,1,0]
	s_nop 0
	v_pk_mul_f32 v[40:41], v[42:43], v[40:41]
	s_nop 0
	v_pk_fma_f32 v[38:39], v[38:39], s[42:43], v[40:41] op_sel_hi:[1,0,1]
	v_pk_fma_f32 v[40:41], v[36:37], s[44:45], v[16:17] op_sel_hi:[1,0,0]
	s_nop 0
	v_pk_fma_f32 v[40:41], v[36:37], v[40:41], s[46:47] op_sel_hi:[1,1,0]
	s_nop 0
	v_pk_fma_f32 v[40:41], v[36:37], v[40:41], s[48:49] op_sel_hi:[1,1,0]
	s_nop 0
	v_pk_fma_f32 v[40:41], v[36:37], v[40:41], s[50:51] op_sel_hi:[1,1,0]
	s_nop 0
	v_pk_fma_f32 v[36:37], v[36:37], v[40:41], 1.0 op_sel_hi:[1,1,0]
	v_and_b32_e32 v40, 1, v52
	v_cndmask_b32_e32 v33, v37, v39, vcc
	v_lshlrev_b32_e32 v37, 30, v51
	v_cmp_eq_u32_e32 vcc, 0, v40
	v_and_b32_e32 v37, 0x80000000, v37
	v_xor_b32_e32 v13, v13, v37
	v_cndmask_b32_e32 v36, v36, v38, vcc
	v_lshlrev_b32_e32 v38, 30, v52
	v_and_b32_e32 v38, 0x80000000, v38
	v_xor_b32_e32 v13, v13, v33
	v_cmp_class_f32_e32 vcc, v11, v242
	v_xor_b32_e32 v12, v12, v38
	v_xor_b32_e32 v12, v12, v36
	v_cndmask_b32_e32 v37, v204, v13, vcc
	v_cmp_class_f32_e32 vcc, v10, v242
	v_pk_mul_f32 v[10:11], v[6:7], 0.5 op_sel_hi:[1,0]
	v_xor_b32_e32 v7, v7, v3
	v_floor_f32_e32 v13, v11
	v_cndmask_b32_e32 v36, v204, v12, vcc
	v_floor_f32_e32 v12, v10
	v_sub_f32_e32 v13, v11, v13
	v_sub_f32_e32 v12, v10, v12
	v_min_f32_e32 v13, 0x3f7fffff, v13
	v_cmp_u_f32_e32 vcc, v11, v11
	v_min_f32_e32 v12, 0x3f7fffff, v12
	ds_write_b128 v87, v[34:37] offset:25344
	v_cndmask_b32_e32 v13, v13, v11, vcc
	v_cmp_u_f32_e32 vcc, v10, v10
	v_xor_b32_e32 v6, v6, v2
	s_nop 0
	v_cndmask_b32_e32 v12, v12, v10, vcc
	v_pk_add_f32 v[12:13], v[12:13], v[12:13]
	v_cmp_class_f32_e32 vcc, v10, v239
	s_nop 1
	v_cndmask_b32_e64 v10, v12, 0, vcc
	v_cmp_class_f32_e32 vcc, v11, v239
	s_nop 1
	v_cndmask_b32_e64 v11, v13, 0, vcc
	v_cndmask_b32_e64 v11, |v3|, v11, s[0:1]
	v_cmp_gt_f32_e64 s[0:1], |v2|, 1.0
	v_add_f32_e32 v13, v11, v11
	v_rndne_f32_e32 v13, v13
	v_cndmask_b32_e64 v10, |v2|, v10, s[0:1]
	v_add_f32_e32 v12, v10, v10
	v_rndne_f32_e32 v12, v12
	v_pk_fma_f32 v[10:11], v[12:13], -0.5, v[10:11] op_sel_hi:[1,0,1]
	v_cvt_i32_f32_e32 v33, v13
	v_cvt_i32_f32_e32 v38, v12
	v_pk_mul_f32 v[12:13], v[10:11], v[10:11]
	v_cmp_gt_f32_e64 s[0:1], |v5|, 1.0
	v_pk_fma_f32 v[34:35], v[12:13], s[36:37], v[14:15] op_sel_hi:[1,0,0]
	v_pk_mul_f32 v[36:37], v[10:11], v[12:13]
	v_pk_fma_f32 v[34:35], v[12:13], v[34:35], s[38:39] op_sel_hi:[1,1,0]
	s_nop 0
	v_pk_fma_f32 v[34:35], v[12:13], v[34:35], s[40:41] op_sel_hi:[1,1,0]
	s_nop 0
	v_pk_mul_f32 v[34:35], v[36:37], v[34:35]
	s_nop 0
	v_pk_fma_f32 v[10:11], v[10:11], s[42:43], v[34:35] op_sel_hi:[1,0,1]
; __device__ __forceinline__ void ph_filtergen(KP p, int l, unsigned char* sm, int wv) {
;     ...
;             for (int i = 0; i < 8; ++i) h2[lane * 68 + wid * 8 + i] = sinpif(f2[wid * 8 + i] * a[i] * 0.3183098861837907f);
;         }
;         __syncthreads();
;     ...
;             for (int e = tid; e < 256 * 64; e += 512) {
;                 const int ol2 = e >> 6, pos = e & 63, o2 = pass * 256 + ol2, c = o2 & 511, n = n0 + pos;
;                 const float tt = (float)n / (float)(L - 1);
;                 const float delta = fabsf(-3.070113457325394f + (float)c * ((-15.350567286626971f + 3.070113457325394f) / 511.0f));
	v_pk_fma_f32 v[34:35], v[12:13], s[44:45], v[16:17] op_sel_hi:[1,0,0]
	s_nop 0
	v_pk_fma_f32 v[34:35], v[12:13], v[34:35], s[46:47] op_sel_hi:[1,1,0]
	s_nop 0
	v_pk_fma_f32 v[34:35], v[12:13], v[34:35], s[48:49] op_sel_hi:[1,1,0]
	s_nop 0
	v_pk_fma_f32 v[34:35], v[12:13], v[34:35], s[50:51] op_sel_hi:[1,1,0]
	s_nop 0
	v_pk_fma_f32 v[12:13], v[12:13], v[34:35], 1.0 op_sel_hi:[1,1,0]
	v_and_b32_e32 v34, 1, v33
	v_and_b32_e32 v35, 1, v38
	v_cmp_eq_u32_e32 vcc, 0, v34
	s_nop 1
	v_cndmask_b32_e32 v11, v13, v11, vcc
	v_cmp_eq_u32_e32 vcc, 0, v35
	v_lshlrev_b32_e32 v13, 30, v38
	v_and_b32_e32 v13, 0x80000000, v13
	v_cndmask_b32_e32 v10, v12, v10, vcc
	v_lshlrev_b32_e32 v12, 30, v33
	v_and_b32_e32 v12, 0x80000000, v12
	v_xor_b32_e32 v7, v7, v12
	v_xor_b32_e32 v6, v6, v13
	v_xor_b32_e32 v7, v7, v11
	v_cmp_class_f32_e32 vcc, v3, v242
	v_xor_b32_e32 v6, v6, v10
	s_nop 0
	v_cndmask_b32_e32 v3, v204, v7, vcc
	v_cmp_class_f32_e32 vcc, v2, v242
	v_and_b32_e32 v7, 0x7fffffff, v5
	s_nop 0
	v_cndmask_b32_e32 v2, v204, v6, vcc
	v_and_b32_e32 v6, 0x7fffffff, v4
	v_pk_mul_f32 v[8:9], v[6:7], 0.5 op_sel_hi:[1,0]
	v_xor_b32_e32 v7, v7, v5
	v_floor_f32_e32 v11, v9
	v_floor_f32_e32 v10, v8
	v_sub_f32_e32 v11, v9, v11
	v_sub_f32_e32 v10, v8, v10
	v_min_f32_e32 v11, 0x3f7fffff, v11
	v_cmp_u_f32_e32 vcc, v9, v9
	v_min_f32_e32 v10, 0x3f7fffff, v10
	v_xor_b32_e32 v6, v6, v4
	v_cndmask_b32_e32 v11, v11, v9, vcc
	v_cmp_u_f32_e32 vcc, v8, v8
	s_nop 1
	v_cndmask_b32_e32 v10, v10, v8, vcc
	v_pk_add_f32 v[10:11], v[10:11], v[10:11]
	v_cmp_class_f32_e32 vcc, v8, v239
	s_nop 1
	v_cndmask_b32_e64 v8, v10, 0, vcc
	v_cmp_class_f32_e32 vcc, v9, v239
	s_nop 1
	v_cndmask_b32_e64 v9, v11, 0, vcc
	v_cndmask_b32_e64 v9, |v5|, v9, s[0:1]
	v_cmp_gt_f32_e64 s[0:1], |v4|, 1.0
	v_add_f32_e32 v11, v9, v9
	v_rndne_f32_e32 v11, v11
	v_cndmask_b32_e64 v8, |v4|, v8, s[0:1]
	v_add_f32_e32 v10, v8, v8
	v_rndne_f32_e32 v10, v10
	v_pk_fma_f32 v[8:9], v[10:11], -0.5, v[8:9] op_sel_hi:[1,0,1]
	v_cvt_i32_f32_e32 v33, v11
	v_cvt_i32_f32_e32 v34, v10
	v_pk_mul_f32 v[10:11], v[8:9], v[8:9]
	s_add_i32 s0, s14, -1
	v_pk_fma_f32 v[12:13], v[10:11], s[36:37], v[14:15] op_sel_hi:[1,0,0]
	v_pk_mul_f32 v[14:15], v[8:9], v[10:11]
	v_pk_fma_f32 v[12:13], v[10:11], v[12:13], s[38:39] op_sel_hi:[1,1,0]
	s_nop 0
	v_pk_fma_f32 v[12:13], v[10:11], v[12:13], s[40:41] op_sel_hi:[1,1,0]
	s_nop 0
	v_pk_mul_f32 v[12:13], v[14:15], v[12:13]
	s_nop 0
	v_pk_fma_f32 v[8:9], v[8:9], s[42:43], v[12:13] op_sel_hi:[1,0,1]
	v_pk_fma_f32 v[12:13], v[10:11], s[44:45], v[16:17] op_sel_hi:[1,0,0]
	s_nop 0
	v_pk_fma_f32 v[12:13], v[10:11], v[12:13], s[46:47] op_sel_hi:[1,1,0]
	s_nop 0
	v_pk_fma_f32 v[12:13], v[10:11], v[12:13], s[48:49] op_sel_hi:[1,1,0]
	s_nop 0
	v_pk_fma_f32 v[12:13], v[10:11], v[12:13], s[50:51] op_sel_hi:[1,1,0]
	s_nop 0
	v_pk_fma_f32 v[10:11], v[10:11], v[12:13], 1.0 op_sel_hi:[1,1,0]
	v_and_b32_e32 v12, 1, v33
	v_and_b32_e32 v13, 1, v34
	v_cmp_eq_u32_e32 vcc, 0, v12
	s_nop 1
	v_cndmask_b32_e32 v9, v11, v9, vcc
	v_cmp_eq_u32_e32 vcc, 0, v13
	v_lshlrev_b32_e32 v11, 30, v34
	v_and_b32_e32 v11, 0x80000000, v11
	v_cndmask_b32_e32 v8, v10, v8, vcc
	v_lshlrev_b32_e32 v10, 30, v33
	v_and_b32_e32 v10, 0x80000000, v10
	v_xor_b32_e32 v7, v7, v10
	v_xor_b32_e32 v6, v6, v11
	v_xor_b32_e32 v7, v7, v9
	v_cmp_class_f32_e32 vcc, v5, v242
	v_xor_b32_e32 v6, v6, v8
	v_ashrrev_i32_e32 v33, 31, v32
	v_cndmask_b32_e32 v5, v204, v7, vcc
	v_cmp_class_f32_e32 vcc, v4, v242
	s_nop 1
	v_cndmask_b32_e32 v4, v204, v6, vcc
	ds_write_b128 v87, v[2:5] offset:25360
	v_cvt_f32_u32_e32 v2, s0
	s_and_b64 s[0:1], s[8:9], exec
	s_cselect_b32 s42, 15, 14
	v_cmp_eq_u32_e64 s[8:9], 0, v32
	v_div_scale_f32 v3, s[0:1], v2, v2, -v0
	v_rcp_f32_e32 v4, v3
	v_cmp_lt_i32_e64 s[0:1], 0, v32
	s_waitcnt lgkmcnt(0)
	s_barrier
	v_fma_f32 v5, -v3, v4, 1.0
	v_fmac_f32_e32 v4, v5, v4
	v_div_scale_f32 v5, vcc, -v0, v2, -v0
	v_mul_f32_e32 v6, v5, v4
	v_fma_f32 v7, -v3, v6, v5
	v_fmac_f32_e32 v6, v7, v4
	v_fma_f32 v3, -v3, v6, v5
	v_div_fmas_f32 v3, v3, v4, v6
	v_div_fixup_f32 v94, v3, v2, -v0
	v_sub_u32_e32 v2, s18, v32
	v_ashrrev_i32_e32 v3, 31, v2
	s_branch .LBB0_892
